# v50 + down-projection GEMM processes its two tile rounds in reverse order so it reads the most recently written half of H first (infinity-cache reuse)
# speedup vs baseline: 1.0040x; 1.0030x over previous
.LBB0_1053:
	s_or_b64 exec, exec, s[2:3]
	v_readlane_b32 s46, v249, 35
	s_waitcnt lgkmcnt(0)
	s_barrier
	s_and_b64 vcc, exec, s[0:1]
	v_readfirstlane_b32 s6, v202
	v_readlane_b32 s47, v249, 36
	s_cbranch_vccnz .LBB0_1077
	s_add_i32 s12, s64, 0x100
	s_cmp_eq_u32 s88, 0x100
	s_cselect_b32 s12, s12, s64
	s_ashr_i32 s24, s64, 31
	s_lshr_b32 s0, s24, 29
	s_add_i32 s4, s12, s0
	s_and_b32 s0, s4, -8
	s_sub_i32 s3, s12, s0
	s_cmp_gt_i32 s3, -1
	s_cbranch_scc0 .LBB0_1056
	s_lshl_b32 s2, s3, 6
	s_ashr_i32 s0, s4, 3
	s_cbranch_execz .LBB0_1057
	s_branch .LBB0_1058

.LBB0_1063:
	s_add_i32 s29, s29, 1
	s_mul_i32 s0, s29, s33
	s_mul_hi_u32 s1, s29, s88
	s_add_i32 s1, s1, s0
	s_mul_i32 s0, s29, s88
	s_add_u32 s12, s0, s64
	s_addc_u32 s13, s1, s24
	v_cmp_gt_i64_e32 vcc, s[12:13], v[138:139]
	v_cmp_lt_i64_e64 s[0:1], s[12:13], v[136:137]
	s_cbranch_vccnz .LBB0_1069
	s_lshl_b32 s8, s64, 1
	s_add_i32 s8, s8, s88
	s_sub_i32 s8, s8, s12
	s_cmp_eq_u32 s88, 0x100
	s_cselect_b32 s12, s8, s12
	s_ashr_i32 s8, s12, 31
	s_lshr_b32 s8, s8, 29
	s_add_i32 s10, s12, s8
	s_and_b32 s8, s10, -8
	s_sub_i32 s11, s12, s8
	s_cmp_gt_i32 s11, -1
	s_mov_b64 s[8:9], -1
	s_cbranch_scc0 .LBB0_1066
	s_lshl_b32 s12, s11, 6
	s_mov_b64 s[8:9], 0
